# GLA chunk scan phase hand-rewritten: saddr addressing, loads interleaved with MFMAs after barrier, batched LDS reads, vT fragment reuse
# speedup vs baseline: 1.0164x; 1.0160x over previous
; __device__ __forceinline__ void gla_scan_phase(const Params& p, int j, bool need_ctx, char* smem, int tid, int bid) {
;     ...
;   for (int unit = bid; unit < 256; unit += gridDim.x) {
;     int dir, dvs, h, b;
;     if (gridDim.x == 256) { const int g = (unit & 7) * 8 + (unit >> 5); dvs = (unit >> 3) & 3; dir = g & 1; h = (g >> 1) & 3; b = g >> 3; }
;     else { dir = unit & 1; dvs = (unit >> 1) & 3; h = (unit >> 3) & 3; b = unit >> 5; }
;     const int dvc = tid & 63, tg = tid >> 6;
;     f32x16 Sacc;
; #pragma unroll
;     for (int r = 0; r < 16; ++r) Sacc[r] = 0.f;
;     __syncthreads();
;     { u32x4 z = {0u, 0u, 0u, 0u}; *(u32x4*)(STL + tid * 32) = z; *(u32x4*)(STL + tid * 32 + 16) = z; }
;     u32x4 qx[2], kx[2]; unsigned kt[16], vv[8]; float ebv = 0.f;
;     const u16* QB = (const u16*)(p.ws + OFF_GQB);
;     const u16* KB2 = (const u16*)((const char*)p.out + OUT_GKB);
;     const float* EBE = (const float*)((const char*)p.out + OUT_EBE);
;     const u16* qsrc = dir ? QB + h * 128 : P + h * 128;
;     const u16* ksrc = dir ? KB2 + h * 128 : P + 512 + h * 128;
;     const long rst = dir ? 512 : LDP;
;     const long sgn = dir ? -1 : 1;
.LBB0_622:
	s_andn2_b64 vcc, exec, s[0:1]
	s_cbranch_vccnz .LBB0_865
	s_cmp_lt_i32 s64, 2
	s_mov_b64 s[0:1], -1
	s_cbranch_scc1 .LBB0_747
	s_cmp_gt_i32 s64, 2
	s_cbranch_scc0 .LBB0_674
	s_cmpk_gt_i32 s62, 0xff
	s_cbranch_scc1 .LBB0_673
	s_mov_b32 s53, s62
	s_cmp_eq_u32 s78, 4
	s_cselect_b32 s60, 1, 0
.Lgs_unit:
	s_cmpk_eq_i32 s71, 0x100
	s_cbranch_scc0 .Lgs_map_plain
	s_and_b32 s0, s53, 7
	s_lshl_b32 s0, s0, 3
	s_lshr_b32 s1, s53, 5
	s_add_u32 s0, s0, s1
	s_lshr_b32 s72, s53, 3
	s_and_b32 s72, s72, 3
	s_and_b32 s55, s0, 1
	s_lshr_b32 s73, s0, 1
	s_and_b32 s73, s73, 3
	s_lshr_b32 s35, s0, 3
	s_branch .Lgs_map_done
.Lgs_map_plain:
	s_and_b32 s55, s53, 1
	s_lshr_b32 s72, s53, 1
	s_and_b32 s72, s72, 3
	s_lshr_b32 s73, s53, 3
	s_and_b32 s73, s73, 3
	s_lshr_b32 s35, s53, 5
.Lgs_map_done:
	v_readlane_b32 s0, v253, 28
	v_readlane_b32 s1, v253, 29
	v_readlane_b32 s4, v253, 43
	v_readlane_b32 s5, v253, 44
	v_readlane_b32 s8, v253, 45
	v_readlane_b32 s9, v253, 46
	v_readlane_b32 s10, v253, 47
	v_readlane_b32 s11, v253, 48
	v_readlane_b32 s18, v253, 41
	v_readlane_b32 s19, v253, 42
	s_movk_i32 s16, 0x400
	s_cmp_eq_u32 s55, 0
	s_cselect_b32 s34, 0x1840, s16
	s_cselect_b32 s80, 0, 63
	s_cselect_b32 s22, s92, s0
	s_cselect_b32 s23, s93, s1
	s_cselect_b32 s24, s4, s8
	s_cselect_b32 s25, s5, s9
	s_cselect_b32 s30, s12, s18
	s_cselect_b32 s31, s13, s19
	s_lshl_b32 s16, s73, 8
	s_add_u32 s22, s22, s16
	s_addc_u32 s23, s23, 0
	s_add_u32 s24, s24, s16
	s_addc_u32 s25, s25, 0
	s_lshl_b32 s0, s73, 9
	s_lshl_b32 s1, s72, 7
	s_add_u32 s0, s0, s1
	s_add_u32 s30, s30, s0
	s_addc_u32 s31, s31, 0
	s_add_u32 s0, s0, 0x800
	s_add_u32 s26, s92, s0
	s_addc_u32 s27, s93, 0
	s_mul_i32 s4, s55, 0x110000
	s_lshl_b32 s5, s73, 9
	s_add_u32 s4, s4, s5
	s_add_u32 s28, s10, s4
	s_addc_u32 s29, s11, 0
	v_and_b32_e32 v100, 63, v203
	v_lshrrev_b32_e32 v101, 6, v203
	v_and_b32_e32 v102, 31, v203
	v_bfe_u32 v103, v203, 5, 1
	v_and_b32_e32 v104, 15, v203
	v_bfe_u32 v105, v203, 1, 3
	v_readfirstlane_b32 s0, v101
	s_mov_b32 s81, s0
	s_lshr_b32 s1, s0, 1
	s_and_b32 s77, s1, 1
	s_and_b32 s4, s0, 1
	s_cmp_gt_u32 s0, 3
	s_cselect_b32 s76, 2, 0
	s_cmp_eq_u32 s0, 1
	s_cselect_b32 s76, 1, s76
	s_lshl_b32 s5, s4, 13
	s_lshl_b32 s8, s77, 13
	s_add_u32 s9, s5, 0x4000
	s_add_u32 s10, s5, 0x12000
	s_cmp_eq_u32 s76, 2
	s_cselect_b32 s72, s8, s9
	s_cselect_b32 s73, s10, s8
	v_xor_b32_e32 v107, v103, v104
	v_lshlrev_b32_e32 v107, 4, v107
	v_lshl_or_b32 v107, v102, 8, v107
	v_add_u32_e32 v108, s72, v107
	v_add_u32_e32 v109, s73, v107
	v_xor_b32_e32 v220, 0, v108
	v_xor_b32_e32 v228, 0, v109
	v_xor_b32_e32 v221, 32, v108
	v_xor_b32_e32 v229, 32, v109
	v_xor_b32_e32 v222, 64, v108
	v_xor_b32_e32 v230, 64, v109
	v_xor_b32_e32 v223, 96, v108
	v_xor_b32_e32 v231, 96, v109
	v_xor_b32_e32 v224, 128, v108
	v_xor_b32_e32 v232, 128, v109
	v_xor_b32_e32 v225, 160, v108
	v_xor_b32_e32 v233, 160, v109
	v_xor_b32_e32 v226, 192, v108
	v_xor_b32_e32 v234, 192, v109
	v_xor_b32_e32 v227, 224, v108
	v_xor_b32_e32 v235, 224, v109
	v_xor_b32_e32 v107, v103, v105
	v_lshlrev_b32_e32 v107, 4, v107
	v_lshl_or_b32 v107, v102, 7, v107
	s_lshl_b32 s9, s1, 12
	s_add_u32 s9, s9, 0x8000
	v_add_u32_e32 v108, s9, v107
	s_lshl_b32 s9, s4, 12
	s_add_u32 s9, s9, 0xc000
	v_add_u32_e32 v109, s9, v107
	v_xor_b32_e32 v236, 0, v108
	v_xor_b32_e32 v245, 0, v109
	v_xor_b32_e32 v237, 32, v108
	v_xor_b32_e32 v246, 32, v109
	v_xor_b32_e32 v243, 64, v108
	v_xor_b32_e32 v247, 64, v109
	v_xor_b32_e32 v244, 96, v108
	v_xor_b32_e32 v248, 96, v109
	s_lshl_b32 s9, s77, 12
	s_add_u32 s9, s9, 0x10000
	v_add_u32_e32 v249, s9, v107
	s_lshl_b32 s8, s4, 2
	v_xor_b32_e32 v108, s8, v105
	v_lshlrev_b32_e32 v108, 4, v108
	v_lshl_or_b32 v108, v102, 7, v108
	v_lshl_or_b32 v108, v103, 3, v108
	v_add_u32_e32 v108, s9, v108
	s_cmp_eq_u32 s76, 2
	s_cbranch_scc1 .Lgs_sclw_done
	v_mov_b32_e32 v249, v108
.Lgs_sclw_done:
	s_lshl_b32 s8, s1, 2
	v_xor_b32_e32 v108, s8, v104
	v_lshlrev_b32_e32 v108, 4, v108
	v_lshl_or_b32 v108, v102, 8, v108
	v_lshl_or_b32 v108, v103, 3, v108
	s_add_u32 s9, s5, 0x12000
	v_add_u32_e32 v250, s9, v108
	s_lshl_b32 s9, s1, 7
	s_add_u32 s9, s9, 0x16000
	v_lshlrev_b32_e32 v108, 4, v103
	v_add_u32_e32 v252, s9, v108
	v_lshrrev_b32_e32 v106, 3, v203
	v_and_b32_e32 v107, 7, v203
	v_and_b32_e32 v108, 15, v106
	v_xor_b32_e32 v108, v107, v108
	v_lshlrev_b32_e32 v108, 4, v108
	v_lshl_or_b32 v192, v106, 8, v108
	v_xor_b32_e32 v193, 0x80, v192
	v_and_b32_e32 v108, 0x7f, v203
	v_lshrrev_b32_e32 v109, 7, v203
	v_bfe_u32 v198, v203, 1, 3
	v_xor_b32_e32 v198, v109, v198
	v_lshlrev_b32_e32 v198, 4, v198
	v_lshl_or_b32 v194, v108, 7, v198
	v_xor_b32_e32 v195, 64, v194
	v_bfe_u32 v198, v203, 1, 3
	v_xor_b32_e32 v198, v101, v198
	v_lshlrev_b32_e32 v198, 4, v198
	v_lshl_or_b32 v196, v100, 7, v198
	v_add_u32_e32 v196, 0xc000, v196
	v_lshlrev_b32_e32 v191, 2, v203
	v_add_u32_e32 v197, 0x16000, v191
	v_xor_b32_e32 v198, s80, v106
	v_mul_lo_u32 v198, v198, s34
	v_lshl_add_u32 v166, v107, 4, v198
	v_lshlrev_b32_e32 v108, 1, v108
	v_lshlrev_b32_e32 v109, 3, v109
	v_add_u32_e32 v198, 0, v109
	v_xor_b32_e32 v198, s80, v198
	v_mul_lo_u32 v198, v198, s34
	v_add_u32_e32 v167, v108, v198
	v_add_u32_e32 v198, 1, v109
	v_xor_b32_e32 v198, s80, v198
	v_mul_lo_u32 v198, v198, s34
	v_add_u32_e32 v168, v108, v198
	v_add_u32_e32 v198, 2, v109
	v_xor_b32_e32 v198, s80, v198
	v_mul_lo_u32 v198, v198, s34
	v_add_u32_e32 v169, v108, v198
	v_add_u32_e32 v198, 3, v109
	v_xor_b32_e32 v198, s80, v198
	v_mul_lo_u32 v198, v198, s34
	v_add_u32_e32 v170, v108, v198
	v_add_u32_e32 v198, 4, v109
	v_xor_b32_e32 v198, s80, v198
	v_mul_lo_u32 v198, v198, s34
	v_add_u32_e32 v171, v108, v198
; __device__ __forceinline__ u16 f2bf(float x) { return (u16)(cvtpk(x, 0.f) & 0xffffu); }
; __device__ __forceinline__ int crow(int r, int hi) { return (r & 3) + 8 * (r >> 2) + 4 * hi; }
; __device__ __forceinline__ void gla_scan_phase(const Params& p, int j, bool need_ctx, char* smem, int tid, int bid) {
;     ...
;           u16* O = dir ? OB : OF;
; #pragma unroll
;           for (int r = 0; r < 16; ++r) {
;             const int pos = c * 64 + tbo * 32 + crow(r, hi);
;             const int tok = dir ? TT - 1 - pos : pos;
;             O[(size_t)(base + tok) * 1024 + h * 256 + dvs * 64 + dvbo * 32 + l32] = f2bf(oacc[r]);
;           }
	v_add_u32_e32 v198, 5, v109
	v_xor_b32_e32 v198, s80, v198
	v_mul_lo_u32 v198, v198, s34
	v_add_u32_e32 v172, v108, v198
	v_add_u32_e32 v198, 6, v109
	v_xor_b32_e32 v198, s80, v198
	v_mul_lo_u32 v198, v198, s34
	v_add_u32_e32 v173, v108, v198
	v_add_u32_e32 v198, 7, v109
	v_xor_b32_e32 v198, s80, v198
	v_mul_lo_u32 v198, v198, s34
	v_add_u32_e32 v174, v108, v198
	v_add_u32_e32 v198, 32, v109
	v_xor_b32_e32 v198, s80, v198
	v_mul_lo_u32 v198, v198, s34
	v_add_u32_e32 v175, v108, v198
	v_add_u32_e32 v198, 33, v109
	v_xor_b32_e32 v198, s80, v198
	v_mul_lo_u32 v198, v198, s34
	v_add_u32_e32 v176, v108, v198
	v_add_u32_e32 v198, 34, v109
	v_xor_b32_e32 v198, s80, v198
	v_mul_lo_u32 v198, v198, s34
	v_add_u32_e32 v177, v108, v198
	v_add_u32_e32 v198, 35, v109
	v_xor_b32_e32 v198, s80, v198
	v_mul_lo_u32 v198, v198, s34
	v_add_u32_e32 v178, v108, v198
	v_add_u32_e32 v198, 36, v109
	v_xor_b32_e32 v198, s80, v198
	v_mul_lo_u32 v198, v198, s34
	v_add_u32_e32 v179, v108, v198
	v_add_u32_e32 v198, 37, v109
	v_xor_b32_e32 v198, s80, v198
	v_mul_lo_u32 v198, v198, s34
	v_add_u32_e32 v180, v108, v198
	v_add_u32_e32 v198, 38, v109
	v_xor_b32_e32 v198, s80, v198
	v_mul_lo_u32 v198, v198, s34
	v_add_u32_e32 v181, v108, v198
	v_add_u32_e32 v198, 39, v109
	v_xor_b32_e32 v198, s80, v198
	v_mul_lo_u32 v198, v198, s34
	v_add_u32_e32 v182, v108, v198
	v_lshlrev_b32_e32 v108, 1, v100
	v_lshlrev_b32_e32 v109, 3, v101
	s_movk_i32 s9, 0x1840
	v_add_u32_e32 v198, 0, v109
	v_xor_b32_e32 v198, s80, v198
	v_mul_lo_u32 v198, v198, s9
	v_add_u32_e32 v183, v108, v198
	v_add_u32_e32 v198, 1, v109
	v_xor_b32_e32 v198, s80, v198
	v_mul_lo_u32 v198, v198, s9
	v_add_u32_e32 v184, v108, v198
	v_add_u32_e32 v198, 2, v109
	v_xor_b32_e32 v198, s80, v198
	v_mul_lo_u32 v198, v198, s9
	v_add_u32_e32 v185, v108, v198
	v_add_u32_e32 v198, 3, v109
	v_xor_b32_e32 v198, s80, v198
	v_mul_lo_u32 v198, v198, s9
	v_add_u32_e32 v186, v108, v198
	v_add_u32_e32 v198, 4, v109
	v_xor_b32_e32 v198, s80, v198
	v_mul_lo_u32 v198, v198, s9
	v_add_u32_e32 v187, v108, v198
	v_add_u32_e32 v198, 5, v109
	v_xor_b32_e32 v198, s80, v198
	v_mul_lo_u32 v198, v198, s9
	v_add_u32_e32 v188, v108, v198
	v_add_u32_e32 v198, 6, v109
	v_xor_b32_e32 v198, s80, v198
	v_mul_lo_u32 v198, v198, s9
	v_add_u32_e32 v189, v108, v198
	v_add_u32_e32 v198, 7, v109
	v_xor_b32_e32 v198, s80, v198
	v_mul_lo_u32 v198, v198, s9
	v_add_u32_e32 v190, v108, v198
	s_cmp_eq_u32 s76, 2
	s_cbranch_scc0 .Lgs_masks
	s_lshl_b32 s9, s77, 5
	v_lshl_add_u32 v109, v103, 2, s9
	s_lshl_b32 s9, s4, 6
	v_lshl_add_u32 v108, v102, 1, s9
	v_add_u32_e32 v198, 0, v109
	v_xor_b32_e32 v198, s80, v198
	v_lshl_add_u32 v204, v198, 11, v108
	v_add_u32_e32 v198, 1, v109
	v_xor_b32_e32 v198, s80, v198
	v_lshl_add_u32 v205, v198, 11, v108
	v_add_u32_e32 v198, 2, v109
	v_xor_b32_e32 v198, s80, v198
	v_lshl_add_u32 v206, v198, 11, v108
	v_add_u32_e32 v198, 3, v109
	v_xor_b32_e32 v198, s80, v198
	v_lshl_add_u32 v207, v198, 11, v108
	v_add_u32_e32 v198, 8, v109
	v_xor_b32_e32 v198, s80, v198
	v_lshl_add_u32 v208, v198, 11, v108
	v_add_u32_e32 v198, 9, v109
	v_xor_b32_e32 v198, s80, v198
	v_lshl_add_u32 v209, v198, 11, v108
	v_add_u32_e32 v198, 10, v109
	v_xor_b32_e32 v198, s80, v198
	v_lshl_add_u32 v210, v198, 11, v108
	v_add_u32_e32 v198, 11, v109
	v_xor_b32_e32 v198, s80, v198
	v_lshl_add_u32 v211, v198, 11, v108
	v_add_u32_e32 v198, 16, v109
	v_xor_b32_e32 v198, s80, v198
	v_lshl_add_u32 v212, v198, 11, v108
	v_add_u32_e32 v198, 17, v109
	v_xor_b32_e32 v198, s80, v198
	v_lshl_add_u32 v213, v198, 11, v108
	v_add_u32_e32 v198, 18, v109
	v_xor_b32_e32 v198, s80, v198
	v_lshl_add_u32 v214, v198, 11, v108
	v_add_u32_e32 v198, 19, v109
	v_xor_b32_e32 v198, s80, v198
	v_lshl_add_u32 v215, v198, 11, v108
	v_add_u32_e32 v198, 24, v109
	v_xor_b32_e32 v198, s80, v198
	v_lshl_add_u32 v216, v198, 11, v108
	v_add_u32_e32 v198, 25, v109
	v_xor_b32_e32 v198, s80, v198
	v_lshl_add_u32 v217, v198, 11, v108
	v_add_u32_e32 v198, 26, v109
	v_xor_b32_e32 v198, s80, v198
	v_lshl_add_u32 v218, v198, 11, v108
	v_add_u32_e32 v198, 27, v109
	v_xor_b32_e32 v198, s80, v198
	v_lshl_add_u32 v219, v198, 11, v108
	s_branch .Lgs_roles_done
; __device__ __forceinline__ void gla_scan_phase(const Params& p, int j, bool need_ctx, char* smem, int tid, int bid) {
;     ...
;     const int dvc = tid & 63, tg = tid >> 6;
;     f32x16 Sacc;
; #pragma unroll
;     for (int r = 0; r < 16; ++r) Sacc[r] = 0.f;
;     __syncthreads();
;     { u32x4 z = {0u, 0u, 0u, 0u}; *(u32x4*)(STL + tid * 32) = z; *(u32x4*)(STL + tid * 32 + 16) = z; }
;     u32x4 qx[2], kx[2]; unsigned kt[16], vv[8]; float ebv = 0.f;
;     const u16* QB = (const u16*)(p.ws + OFF_GQB);
;     const u16* KB2 = (const u16*)((const char*)p.out + OUT_GKB);
;     const float* EBE = (const float*)((const char*)p.out + OUT_EBE);
;     const u16* qsrc = dir ? QB + h * 128 : P + h * 128;
;     const u16* ksrc = dir ? KB2 + h * 128 : P + 512 + h * 128;
;     const long rst = dir ? 512 : LDP;
;     const long sgn = dir ? -1 : 1;
;     ...
;     GLA_PREFETCH(0);
;     for (int ci = 0; ci < 68; ++ci) {
;     ...
;           const int t = tb * 32 + l32;
; #pragma unroll
;           for (int rg = 0; rg < 4; ++rg) {
;             const int s0 = sb * 32 + 8 * rg + 4 * hi;
;             const float v0 = (s0 + 0 <= t) ? sacc[rg * 4 + 0] : 0.f, v1 = (s0 + 1 <= t) ? sacc[rg * 4 + 1] : 0.f;
;             const float v2 = (s0 + 2 <= t) ? sacc[rg * 4 + 2] : 0.f, v3 = (s0 + 3 <= t) ? sacc[rg * 4 + 3] : 0.f;
.Lgs_masks:
	s_lshl_b32 s9, s4, 5
	v_lshl_add_u32 v109, v103, 2, s9
	s_lshl_b32 s9, s77, 5
	v_add_u32_e32 v108, s9, v102
	v_add_u32_e32 v198, 0, v109
	v_cmp_le_u32_e32 vcc, v198, v108
	s_nop 1
	v_cndmask_b32_e64 v204, 0, -1, vcc
	v_add_u32_e32 v198, 1, v109
	v_cmp_le_u32_e32 vcc, v198, v108
	s_nop 1
	v_cndmask_b32_e64 v205, 0, -1, vcc
	v_add_u32_e32 v198, 2, v109
	v_cmp_le_u32_e32 vcc, v198, v108
	s_nop 1
	v_cndmask_b32_e64 v206, 0, -1, vcc
	v_add_u32_e32 v198, 3, v109
	v_cmp_le_u32_e32 vcc, v198, v108
	s_nop 1
	v_cndmask_b32_e64 v207, 0, -1, vcc
	v_add_u32_e32 v198, 8, v109
	v_cmp_le_u32_e32 vcc, v198, v108
	s_nop 1
	v_cndmask_b32_e64 v208, 0, -1, vcc
	v_add_u32_e32 v198, 9, v109
	v_cmp_le_u32_e32 vcc, v198, v108
	s_nop 1
	v_cndmask_b32_e64 v209, 0, -1, vcc
	v_add_u32_e32 v198, 10, v109
	v_cmp_le_u32_e32 vcc, v198, v108
	s_nop 1
	v_cndmask_b32_e64 v210, 0, -1, vcc
	v_add_u32_e32 v198, 11, v109
	v_cmp_le_u32_e32 vcc, v198, v108
	s_nop 1
	v_cndmask_b32_e64 v211, 0, -1, vcc
	v_add_u32_e32 v198, 16, v109
	v_cmp_le_u32_e32 vcc, v198, v108
	s_nop 1
	v_cndmask_b32_e64 v212, 0, -1, vcc
	v_add_u32_e32 v198, 17, v109
	v_cmp_le_u32_e32 vcc, v198, v108
	s_nop 1
	v_cndmask_b32_e64 v213, 0, -1, vcc
	v_add_u32_e32 v198, 18, v109
	v_cmp_le_u32_e32 vcc, v198, v108
	s_nop 1
	v_cndmask_b32_e64 v214, 0, -1, vcc
	v_add_u32_e32 v198, 19, v109
	v_cmp_le_u32_e32 vcc, v198, v108
	s_nop 1
	v_cndmask_b32_e64 v215, 0, -1, vcc
	v_add_u32_e32 v198, 24, v109
	v_cmp_le_u32_e32 vcc, v198, v108
	s_nop 1
	v_cndmask_b32_e64 v216, 0, -1, vcc
	v_add_u32_e32 v198, 25, v109
	v_cmp_le_u32_e32 vcc, v198, v108
	s_nop 1
	v_cndmask_b32_e64 v217, 0, -1, vcc
	v_add_u32_e32 v198, 26, v109
	v_cmp_le_u32_e32 vcc, v198, v108
	s_nop 1
	v_cndmask_b32_e64 v218, 0, -1, vcc
	v_add_u32_e32 v198, 27, v109
	v_cmp_le_u32_e32 vcc, v198, v108
	s_nop 1
	v_cndmask_b32_e64 v219, 0, -1, vcc
.Lgs_roles_done:
	s_waitcnt vmcnt(0) lgkmcnt(0)
	s_barrier
	v_lshlrev_b32_e32 v198, 5, v203
	v_add_u32_e32 v198, 0x12000, v198
	v_mov_b32_e32 v112, 0
	v_mov_b32_e32 v113, 0
	v_mov_b32_e32 v114, 0
	v_mov_b32_e32 v115, 0
	ds_write_b128 v198, v[112:115]
	ds_write_b128 v198, v[112:115] offset:16
	v_mov_b32_e32 v0, 0
	v_mov_b32_e32 v1, 0
	v_mov_b32_e32 v2, 0
	v_mov_b32_e32 v3, 0
	v_mov_b32_e32 v4, 0
	v_mov_b32_e32 v5, 0
	v_mov_b32_e32 v6, 0
	v_mov_b32_e32 v7, 0
	v_mov_b32_e32 v8, 0
	v_mov_b32_e32 v9, 0
	v_mov_b32_e32 v10, 0
	v_mov_b32_e32 v11, 0
	v_mov_b32_e32 v12, 0
	v_mov_b32_e32 v13, 0
	v_mov_b32_e32 v14, 0
	v_mov_b32_e32 v15, 0
	s_mov_b32 s54, 0
	s_add_i32 s1, s54, -4
	s_cmp_lt_u32 s54, 4
	s_cselect_b32 s0, s54, s1
	s_movk_i32 s5, 0x1000
	s_cselect_b32 s1, 0x100, s5
	s_lshl_b32 s4, s35, 8
	s_add_u32 s4, s4, 0x8000
	s_lshl_b32 s5, s35, 12
	s_cmp_lt_u32 s54, 4
	s_cselect_b32 s4, s4, s5
	s_lshl_b32 s0, s0, 6
	s_sub_u32 s1, s1, 64
	s_sub_u32 s1, s1, s0
	s_cmp_eq_u32 s55, 0
	s_cselect_b32 s0, s0, s1
	s_add_u32 s0, s4, s0
	s_mul_i32 s1, s0, s34
	s_add_u32 s6, s22, s1
	s_addc_u32 s7, s23, 0
	s_add_u32 s8, s24, s1
	s_addc_u32 s9, s25, 0
	s_mul_i32 s1, s0, 0x1840
	s_add_u32 s10, s26, s1
	s_addc_u32 s11, s27, 0
	s_lshr_b32 s1, s0, 6
	s_lshl_b32 s1, s1, 11
	s_add_u32 s18, s28, s1
	s_addc_u32 s19, s29, 0
	global_load_dwordx4 v[112:115], v166, s[6:7]
	global_load_dwordx4 v[116:119], v166, s[6:7] offset:128
	global_load_dwordx4 v[120:123], v166, s[8:9]
	global_load_dwordx4 v[124:127], v166, s[8:9] offset:128
	global_load_ushort v128, v167, s[8:9]
	global_load_ushort v129, v168, s[8:9]
	global_load_ushort v130, v169, s[8:9]
	global_load_ushort v131, v170, s[8:9]
	global_load_ushort v132, v171, s[8:9]
	global_load_ushort v133, v172, s[8:9]
	global_load_ushort v134, v173, s[8:9]
	global_load_ushort v135, v174, s[8:9]
	global_load_ushort v136, v175, s[8:9]
	global_load_ushort v137, v176, s[8:9]
	global_load_ushort v138, v177, s[8:9]
	global_load_ushort v139, v178, s[8:9]
	global_load_ushort v140, v179, s[8:9]
	global_load_ushort v141, v180, s[8:9]
	global_load_ushort v142, v181, s[8:9]
	global_load_ushort v143, v182, s[8:9]
	global_load_ushort v144, v183, s[10:11]
	global_load_ushort v145, v184, s[10:11]
	global_load_ushort v146, v185, s[10:11]
	global_load_ushort v147, v186, s[10:11]
	global_load_ushort v148, v187, s[10:11]
	global_load_ushort v149, v188, s[10:11]
	global_load_ushort v150, v189, s[10:11]
	global_load_ushort v151, v190, s[10:11]
	global_load_dword v152, v191, s[18:19]
	s_mov_b32 s97, 0
.Lgs_chunk:
	s_add_i32 s1, s54, -4
	s_cmp_lt_u32 s54, 4
	s_cselect_b32 s0, s54, s1
	s_movk_i32 s5, 0x1000
	s_cselect_b32 s1, 0x100, s5
	s_lshl_b32 s4, s35, 8
	s_add_u32 s4, s4, 0x8000
	s_lshl_b32 s5, s35, 12
	s_cmp_lt_u32 s54, 4
	s_cselect_b32 s4, s4, s5
	s_lshl_b32 s0, s0, 6
	s_sub_u32 s1, s1, 64
	s_sub_u32 s1, s1, s0
	s_cmp_eq_u32 s55, 0
	s_cselect_b32 s0, s0, s1
	s_add_u32 s0, s4, s0
	s_lshl_b32 s1, s0, 11
	s_add_u32 s20, s30, s1
	s_addc_u32 s21, s31, 0
	s_cmp_gt_u32 s54, 3
	s_cselect_b32 s96, 1, s60
	s_cmp_eq_u32 s97, 0
	s_cbranch_scc1 .Lgs_wait0
	s_waitcnt vmcnt(16)
	s_branch .Lgs_waited

; __device__ __forceinline__ void gla_scan_phase(const Params& p, int j, bool need_ctx, char* smem, int tid, int bid) {
;     ...
;       char* vT = vT0 + (ci & 1) * 40960;
;       {
;         if (tid < 128) ebend[tid] = ebv;
;         const int r = tid >> 3, c0 = tid & 7;
;         *(u32x4*)(qbL + swz256(r, c0)) = qx[0]; *(u32x4*)(qbL + swz256(r, c0 + 8)) = qx[1];
;         *(u32x4*)(kinvL + swz256(r, c0)) = kx[0]; *(u32x4*)(kinvL + swz256(r, c0 + 8)) = kx[1];
;         const int kdt = tid & 127, tgk = tid >> 7;
;         u32x4 w0 = {kt[0] | (kt[1] << 16), kt[2] | (kt[3] << 16), kt[4] | (kt[5] << 16), kt[6] | (kt[7] << 16)};
;         u32x4 w1 = {kt[8] | (kt[9] << 16), kt[10] | (kt[11] << 16), kt[12] | (kt[13] << 16), kt[14] | (kt[15] << 16)};
;         *(u32x4*)(kendT + swz128(kdt, tgk)) = w0;
;         *(u32x4*)(kendT + swz128(kdt, tgk + 4)) = w1;
;         u32x4 wv = {vv[0] | (vv[1] << 16), vv[2] | (vv[3] << 16), vv[4] | (vv[5] << 16), vv[6] | (vv[7] << 16)};
;         *(u32x4*)(vT + swz128(dvc, tg)) = wv;
;       }
;       __builtin_amdgcn_sched_barrier(0);
;       if (ci + 1 < 68) GLA_PREFETCH(ci + 1);
;       __builtin_amdgcn_sched_barrier(0);
;       __syncthreads();
;       f32x16 oacc;
; #pragma unroll
;       for (int r = 0; r < 16; ++r) oacc[r] = 0.f;
;       const int tbo = (wid - 4) >> 1, dvbo = (wid - 4) & 1;
;       const bool need_o = !is_ctx || need_ctx;
;       if (!need_o) {
;       } else if (wid < 4) {
;         const int sb = wid & 1, tb = wid >> 1;
;         if (sb <= tb) {
;           f32x16 sacc;
; #pragma unroll
;           for (int r = 0; r < 16; ++r) sacc[r] = 0.f;
;           bf16x8 av[8], bv8[8];
; #pragma unroll
;           for (int k16 = 0; k16 < 8; ++k16) {
;             av[k16] = *(const bf16x8*)(kinvL + swz256(sb * 32 + l32, k16 * 2 + hi));
;             bv8[k16] = *(const bf16x8*)(qbL + swz256(tb * 32 + l32, k16 * 2 + hi));
;           }
; #pragma unroll
;           for (int k16 = 0; k16 < 8; ++k16) sacc = __builtin_amdgcn_mfma_f32_32x32x16_bf16(av[k16], bv8[k16], sacc, 0, 0, 0);
;           const int t = tb * 32 + l32;
; #pragma unroll
;           for (int rg = 0; rg < 4; ++rg) {
;             const int s0 = sb * 32 + 8 * rg + 4 * hi;
;             const float v0 = (s0 + 0 <= t) ? sacc[rg * 4 + 0] : 0.f, v1 = (s0 + 1 <= t) ? sacc[rg * 4 + 1] : 0.f;
.Lgs_waited:
	ds_write_b128 v192, v[112:115]
	ds_write_b128 v193, v[116:119]
	ds_write_b128 v192, v[120:123] offset:16384
	ds_write_b128 v193, v[124:127] offset:16384
	v_lshl_or_b32 v154, v129, 16, v128
	v_lshl_or_b32 v155, v131, 16, v130
	v_lshl_or_b32 v156, v133, 16, v132
	v_lshl_or_b32 v157, v135, 16, v134
	v_lshl_or_b32 v158, v137, 16, v136
	v_lshl_or_b32 v159, v139, 16, v138
	v_lshl_or_b32 v160, v141, 16, v140
	v_lshl_or_b32 v161, v143, 16, v142
	ds_write_b128 v194, v[154:157] offset:32768
	ds_write_b128 v195, v[158:161] offset:32768
	v_lshl_or_b32 v162, v145, 16, v144
	v_lshl_or_b32 v163, v147, 16, v146
	v_lshl_or_b32 v164, v149, 16, v148
	v_lshl_or_b32 v165, v151, 16, v150
	ds_write_b128 v196, v[162:165]
	s_cmp_gt_u32 s81, 1
	s_cbranch_scc1 .Lgs_noeb
	ds_write_b32 v197, v152
.Lgs_noeb:
	s_waitcnt lgkmcnt(0)
	s_barrier
	s_add_u32 s65, s54, 1
	s_min_u32 s65, s65, 67
	s_cmp_eq_u32 s96, 0
	s_cbranch_scc1 .Lgs_s1_nochain
	s_cmp_eq_u32 s76, 1
	s_cbranch_scc1 .Lgs_s1_nochain
	ds_read_b128 v[32:35], v220
	ds_read_b128 v[48:51], v228
	ds_read_b128 v[36:39], v221
	ds_read_b128 v[52:55], v229
	ds_read_b128 v[40:43], v222
	ds_read_b128 v[56:59], v230
	ds_read_b128 v[44:47], v223
	ds_read_b128 v[60:63], v231
	s_add_i32 s1, s65, -4
	s_cmp_lt_u32 s65, 4
	s_cselect_b32 s0, s65, s1
	s_movk_i32 s5, 0x1000
	s_cselect_b32 s1, 0x100, s5
	s_lshl_b32 s4, s35, 8
	s_add_u32 s4, s4, 0x8000
	s_lshl_b32 s5, s35, 12
	s_cmp_lt_u32 s65, 4
	s_cselect_b32 s4, s4, s5
	s_lshl_b32 s0, s0, 6
	s_sub_u32 s1, s1, 64
	s_sub_u32 s1, s1, s0
	s_cmp_eq_u32 s55, 0
	s_cselect_b32 s0, s0, s1
	s_add_u32 s0, s4, s0
	s_mul_i32 s1, s0, s34
	s_add_u32 s6, s22, s1
	s_addc_u32 s7, s23, 0
	s_add_u32 s8, s24, s1
	s_addc_u32 s9, s25, 0
	s_mul_i32 s1, s0, 0x1840
	s_add_u32 s10, s26, s1
	s_addc_u32 s11, s27, 0
	s_lshr_b32 s1, s0, 6
	s_lshl_b32 s1, s1, 11
	s_add_u32 s18, s28, s1
	s_addc_u32 s19, s29, 0
	s_waitcnt lgkmcnt(6)
	v_mfma_f32_32x32x16_bf16 v[16:31], v[32:35], v[48:51], 0
	ds_read_b128 v[32:35], v224
	ds_read_b128 v[48:51], v232
	global_load_dwordx4 v[112:115], v166, s[6:7]
	global_load_dwordx4 v[116:119], v166, s[6:7] offset:128
	global_load_dwordx4 v[120:123], v166, s[8:9]
	global_load_dwordx4 v[124:127], v166, s[8:9] offset:128
	s_waitcnt lgkmcnt(6)
	v_mfma_f32_32x32x16_bf16 v[16:31], v[36:39], v[52:55], v[16:31]
	ds_read_b128 v[36:39], v225
	ds_read_b128 v[52:55], v233
	global_load_ushort v128, v167, s[8:9]
	global_load_ushort v129, v168, s[8:9]
	global_load_ushort v130, v169, s[8:9]
	global_load_ushort v131, v170, s[8:9]
	s_waitcnt lgkmcnt(6)
	v_mfma_f32_32x32x16_bf16 v[16:31], v[40:43], v[56:59], v[16:31]
	ds_read_b128 v[40:43], v226
	ds_read_b128 v[56:59], v234
	global_load_ushort v132, v171, s[8:9]
	global_load_ushort v133, v172, s[8:9]
	global_load_ushort v134, v173, s[8:9]
	global_load_ushort v135, v174, s[8:9]
	s_waitcnt lgkmcnt(6)
	v_mfma_f32_32x32x16_bf16 v[16:31], v[44:47], v[60:63], v[16:31]
	ds_read_b128 v[44:47], v227
	ds_read_b128 v[60:63], v235
	global_load_ushort v136, v175, s[8:9]
	global_load_ushort v137, v176, s[8:9]
	global_load_ushort v138, v177, s[8:9]
	global_load_ushort v139, v178, s[8:9]
	s_waitcnt lgkmcnt(6)
	v_mfma_f32_32x32x16_bf16 v[16:31], v[32:35], v[48:51], v[16:31]
	ds_read_b128 v[64:67], v236
	ds_read_b128 v[80:83], v245
	global_load_ushort v140, v179, s[8:9]
	global_load_ushort v141, v180, s[8:9]
	global_load_ushort v142, v181, s[8:9]
	global_load_ushort v143, v182, s[8:9]
	s_waitcnt lgkmcnt(6)
	v_mfma_f32_32x32x16_bf16 v[16:31], v[36:39], v[52:55], v[16:31]
	ds_read_b128 v[68:71], v237
	ds_read_b128 v[84:87], v246
	global_load_ushort v144, v183, s[10:11]
	global_load_ushort v145, v184, s[10:11]
	global_load_ushort v146, v185, s[10:11]
	global_load_ushort v147, v186, s[10:11]
	s_waitcnt lgkmcnt(6)
	v_mfma_f32_32x32x16_bf16 v[16:31], v[40:43], v[56:59], v[16:31]
	ds_read_b128 v[72:75], v243
	ds_read_b128 v[88:91], v247
	global_load_ushort v148, v187, s[10:11]
	global_load_ushort v149, v188, s[10:11]
	global_load_ushort v150, v189, s[10:11]
	global_load_ushort v151, v190, s[10:11]
	s_waitcnt lgkmcnt(6)
	v_mfma_f32_32x32x16_bf16 v[16:31], v[44:47], v[60:63], v[16:31]
	ds_read_b128 v[76:79], v244
	ds_read_b128 v[92:95], v248
	global_load_dword v152, v191, s[18:19]
	s_branch .Lgs_supd
.Lgs_s1_nochain:
	ds_read_b128 v[64:67], v236
	ds_read_b128 v[80:83], v245
	ds_read_b128 v[68:71], v237
	ds_read_b128 v[84:87], v246
	ds_read_b128 v[72:75], v243
	ds_read_b128 v[88:91], v247
	ds_read_b128 v[76:79], v244
	ds_read_b128 v[92:95], v248
	s_add_i32 s1, s65, -4
	s_cmp_lt_u32 s65, 4
	s_cselect_b32 s0, s65, s1
	s_movk_i32 s5, 0x1000
	s_cselect_b32 s1, 0x100, s5
	s_lshl_b32 s4, s35, 8
	s_add_u32 s4, s4, 0x8000
	s_lshl_b32 s5, s35, 12
	s_cmp_lt_u32 s65, 4
	s_cselect_b32 s4, s4, s5
	s_lshl_b32 s0, s0, 6
	s_sub_u32 s1, s1, 64
	s_sub_u32 s1, s1, s0
	s_cmp_eq_u32 s55, 0
	s_cselect_b32 s0, s0, s1
	s_add_u32 s0, s4, s0
	s_mul_i32 s1, s0, s34
	s_add_u32 s6, s22, s1
	s_addc_u32 s7, s23, 0
	s_add_u32 s8, s24, s1
	s_addc_u32 s9, s25, 0
	s_mul_i32 s1, s0, 0x1840
	s_add_u32 s10, s26, s1
	s_addc_u32 s11, s27, 0
	s_lshr_b32 s1, s0, 6
	s_lshl_b32 s1, s1, 11
	s_add_u32 s18, s28, s1
	s_addc_u32 s19, s29, 0
	global_load_dwordx4 v[112:115], v166, s[6:7]
	global_load_dwordx4 v[116:119], v166, s[6:7] offset:128
	global_load_dwordx4 v[120:123], v166, s[8:9]
	global_load_dwordx4 v[124:127], v166, s[8:9] offset:128
	global_load_ushort v128, v167, s[8:9]
	global_load_ushort v129, v168, s[8:9]
	global_load_ushort v130, v169, s[8:9]
	global_load_ushort v131, v170, s[8:9]
	global_load_ushort v132, v171, s[8:9]
	global_load_ushort v133, v172, s[8:9]
	global_load_ushort v134, v173, s[8:9]
	global_load_ushort v135, v174, s[8:9]
	global_load_ushort v136, v175, s[8:9]
	global_load_ushort v137, v176, s[8:9]
	global_load_ushort v138, v177, s[8:9]
	global_load_ushort v139, v178, s[8:9]
	global_load_ushort v140, v179, s[8:9]
	global_load_ushort v141, v180, s[8:9]
	global_load_ushort v142, v181, s[8:9]
	global_load_ushort v143, v182, s[8:9]
	global_load_ushort v144, v183, s[10:11]
	global_load_ushort v145, v184, s[10:11]
	global_load_ushort v146, v185, s[10:11]
	global_load_ushort v147, v186, s[10:11]
	global_load_ushort v148, v187, s[10:11]
	global_load_ushort v149, v188, s[10:11]
	global_load_ushort v150, v189, s[10:11]
	global_load_ushort v151, v190, s[10:11]
	global_load_dword v152, v191, s[18:19]
; __device__ __forceinline__ u16 f2bf(float x) { return (u16)(cvtpk(x, 0.f) & 0xffffu); }
; __device__ __forceinline__ int crow(int r, int hi) { return (r & 3) + 8 * (r >> 2) + 4 * hi; }
; __device__ __forceinline__ void gla_scan_phase(const Params& p, int j, bool need_ctx, char* smem, int tid, int bid) {
;     ...
;       const int kb = wid >> 1, dvb2 = wid & 1;
;       {
;         bf16x8 av[4], bv4[4];
; #pragma unroll
;         for (int k16 = 0; k16 < 4; ++k16) {
;           av[k16] = *(const bf16x8*)(kendT + swz128(kb * 32 + l32, k16 * 2 + hi));
;           bv4[k16] = *(const bf16x8*)(vT + swz128(dvb2 * 32 + l32, k16 * 2 + hi));
;         }
; #pragma unroll
;         for (int k16 = 0; k16 < 4; ++k16) Sacc = __builtin_amdgcn_mfma_f32_32x32x16_bf16(av[k16], bv4[k16], Sacc, 0, 0, 0);
; #pragma unroll
;         for (int rg = 0; rg < 4; ++rg) {
;           const f32x4 e4 = *(const f32x4*)(ebend + kb * 32 + 8 * rg + 4 * hi);
;           Sacc[rg * 4 + 0] *= e4[0]; Sacc[rg * 4 + 1] *= e4[1]; Sacc[rg * 4 + 2] *= e4[2]; Sacc[rg * 4 + 3] *= e4[3];
;         }
;       }
;       __syncthreads();
;       if (wid >= 4 && need_o) {
; #pragma unroll
;         for (int k16 = 0; k16 < 4; ++k16) {
;           if (k16 < 2 || tbo == 1) {
;             const bf16x8 a = *(const bf16x8*)(scL + swz128(tbo * 32 + l32, k16 * 2 + hi));
;             const bf16x8 bv = *(const bf16x8*)(vT + swz128(dvbo * 32 + l32, k16 * 2 + hi));
;             oacc = __builtin_amdgcn_mfma_f32_32x32x16_bf16(a, bv, oacc, 0, 0, 0);
;           }
;         }
;         if (!is_ctx || need_ctx) {
;           u16* O = dir ? OB : OF;
; #pragma unroll
;           for (int r = 0; r < 16; ++r) {
;             const int pos = c * 64 + tbo * 32 + crow(r, hi);
;             const int tok = dir ? TT - 1 - pos : pos;
;             O[(size_t)(base + tok) * 1024 + h * 256 + dvs * 64 + dvbo * 32 + l32] = f2bf(oacc[r]);
;           }
;         }
;       }
;       {
;         const int dv = dvb2 * 32 + l32;
; #pragma unroll
;         for (int rg = 0; rg < 4; ++rg) {
;           const int k0 = kb * 32 + 8 * rg + 4 * hi;
;           u32x2 w = {cvtpk(Sacc[rg * 4 + 0], Sacc[rg * 4 + 1]), cvtpk(Sacc[rg * 4 + 2], Sacc[rg * 4 + 3])};
;           *(u32x2*)(STL + swz256(dv, k0 >> 3) + (k0 & 7) * 2) = w;
;         }
;       }
.Lgs_supd:
	s_waitcnt lgkmcnt(6)
	v_mfma_f32_32x32x16_bf16 v[0:15], v[64:67], v[80:83], v[0:15]
	s_waitcnt lgkmcnt(4)
	v_mfma_f32_32x32x16_bf16 v[0:15], v[68:71], v[84:87], v[0:15]
	s_waitcnt lgkmcnt(2)
	v_mfma_f32_32x32x16_bf16 v[0:15], v[72:75], v[88:91], v[0:15]
	s_waitcnt lgkmcnt(0)
	v_mfma_f32_32x32x16_bf16 v[0:15], v[76:79], v[92:95], v[0:15]
	ds_read_b128 v[96:99], v252 offset:0
	ds_read_b128 v[100:103], v252 offset:32
	ds_read_b128 v[104:107], v252 offset:64
	ds_read_b128 v[108:111], v252 offset:96
	s_cmp_eq_u32 s96, 0
	s_cbranch_scc1 .Lgs_noscore
	s_cmp_eq_u32 s76, 0
	s_cbranch_scc0 .Lgs_noscore
	s_nop 7
	v_and_b32_e32 v16, v204, v16
	v_and_b32_e32 v17, v205, v17
	v_and_b32_e32 v18, v206, v18
	v_and_b32_e32 v19, v207, v19
	v_and_b32_e32 v20, v208, v20
	v_and_b32_e32 v21, v209, v21
	v_and_b32_e32 v22, v210, v22
	v_and_b32_e32 v23, v211, v23
	v_and_b32_e32 v24, v212, v24
	v_and_b32_e32 v25, v213, v25
	v_and_b32_e32 v26, v214, v26
	v_and_b32_e32 v27, v215, v27
	v_and_b32_e32 v28, v216, v28
	v_and_b32_e32 v29, v217, v29
	v_and_b32_e32 v30, v218, v30
	v_and_b32_e32 v31, v219, v31
	v_cvt_pk_bf16_f32 v154, v16, v17
	v_cvt_pk_bf16_f32 v155, v18, v19
	v_cvt_pk_bf16_f32 v156, v20, v21
	v_cvt_pk_bf16_f32 v157, v22, v23
	v_cvt_pk_bf16_f32 v158, v24, v25
	v_cvt_pk_bf16_f32 v159, v26, v27
	v_cvt_pk_bf16_f32 v160, v28, v29
	v_cvt_pk_bf16_f32 v161, v30, v31
	v_xor_b32_e32 v198, 16, v249
	v_xor_b32_e32 v199, 32, v249
	v_xor_b32_e32 v200, 48, v249
	ds_write_b64 v249, v[154:155]
	ds_write_b64 v198, v[156:157]
	ds_write_b64 v199, v[158:159]
	ds_write_b64 v200, v[160:161]
.Lgs_noscore:
	s_nop 7
	s_nop 3
	s_waitcnt lgkmcnt(0)
	v_mul_f32_e32 v0, v0, v96
	v_mul_f32_e32 v1, v1, v97
	v_mul_f32_e32 v2, v2, v98
	v_mul_f32_e32 v3, v3, v99
	v_mul_f32_e32 v4, v4, v100
	v_mul_f32_e32 v5, v5, v101
	v_mul_f32_e32 v6, v6, v102
	v_mul_f32_e32 v7, v7, v103
	v_mul_f32_e32 v8, v8, v104
	v_mul_f32_e32 v9, v9, v105
	v_mul_f32_e32 v10, v10, v106
	v_mul_f32_e32 v11, v11, v107
	v_mul_f32_e32 v12, v12, v108
	v_mul_f32_e32 v13, v13, v109
	v_mul_f32_e32 v14, v14, v110
	v_mul_f32_e32 v15, v15, v111
	s_barrier
	s_mov_b32 s97, 0
	s_cmp_eq_u32 s96, 0
	s_cbranch_scc1 .Lgs_s2_state
	s_cmp_eq_u32 s76, 2
	s_cbranch_scc0 .Lgs_s2_state
	v_xor_b32_e32 v198, 32, v249
	ds_read_b128 v[96:99], v249
	ds_read_b128 v[100:103], v198
	s_cmp_eq_u32 s77, 0
	s_cbranch_scc1 .Lgs_o_half
	v_xor_b32_e32 v199, 64, v249
	v_xor_b32_e32 v200, 96, v249
	ds_read_b128 v[104:107], v199
	ds_read_b128 v[108:111], v200
	s_waitcnt lgkmcnt(2)
	v_mfma_f32_32x32x16_bf16 v[16:31], v[96:99], v[80:83], v[16:31]
	v_mfma_f32_32x32x16_bf16 v[16:31], v[100:103], v[84:87], v[16:31]
	s_waitcnt lgkmcnt(0)
	v_mfma_f32_32x32x16_bf16 v[16:31], v[104:107], v[88:91], v[16:31]
	v_mfma_f32_32x32x16_bf16 v[16:31], v[108:111], v[92:95], v[16:31]
	s_branch .Lgs_o_store
.Lgs_o_half:
	s_waitcnt lgkmcnt(0)
	v_mfma_f32_32x32x16_bf16 v[16:31], v[96:99], v[80:83], v[16:31]
	v_mfma_f32_32x32x16_bf16 v[16:31], v[100:103], v[84:87], v[16:31]
.Lgs_o_store:
	v_cvt_pk_bf16_f32 v154, v0, v1
	v_cvt_pk_bf16_f32 v155, v2, v3
	v_cvt_pk_bf16_f32 v156, v4, v5
	v_cvt_pk_bf16_f32 v157, v6, v7
	v_cvt_pk_bf16_f32 v158, v8, v9
	v_cvt_pk_bf16_f32 v159, v10, v11
	v_cvt_pk_bf16_f32 v160, v12, v13
	v_cvt_pk_bf16_f32 v161, v14, v15
	v_xor_b32_e32 v198, 16, v250
	v_xor_b32_e32 v199, 32, v250
	v_xor_b32_e32 v200, 48, v250
	ds_write_b64 v250, v[154:155]
	ds_write_b64 v198, v[156:157]
	ds_write_b64 v199, v[158:159]
	ds_write_b64 v200, v[160:161]
	s_nop 3
	v_cvt_pk_bf16_f32 v198, v16, v201
	global_store_short v204, v198, s[20:21]
	v_cvt_pk_bf16_f32 v199, v17, v201
	global_store_short v205, v199, s[20:21]
	v_cvt_pk_bf16_f32 v200, v18, v201
	global_store_short v206, v200, s[20:21]
	v_cvt_pk_bf16_f32 v153, v19, v201
	global_store_short v207, v153, s[20:21]
	v_cvt_pk_bf16_f32 v198, v20, v201
	global_store_short v208, v198, s[20:21]
	v_cvt_pk_bf16_f32 v199, v21, v201
	global_store_short v209, v199, s[20:21]
	v_cvt_pk_bf16_f32 v200, v22, v201
	global_store_short v210, v200, s[20:21]
	v_cvt_pk_bf16_f32 v153, v23, v201
	global_store_short v211, v153, s[20:21]
	v_cvt_pk_bf16_f32 v198, v24, v201
	global_store_short v212, v198, s[20:21]
	v_cvt_pk_bf16_f32 v199, v25, v201
	global_store_short v213, v199, s[20:21]
	v_cvt_pk_bf16_f32 v200, v26, v201
	global_store_short v214, v200, s[20:21]
	v_cvt_pk_bf16_f32 v153, v27, v201
	global_store_short v215, v153, s[20:21]
	v_cvt_pk_bf16_f32 v198, v28, v201
	global_store_short v216, v198, s[20:21]
	v_cvt_pk_bf16_f32 v199, v29, v201
	global_store_short v217, v199, s[20:21]
	v_cvt_pk_bf16_f32 v200, v30, v201
	global_store_short v218, v200, s[20:21]
	v_cvt_pk_bf16_f32 v153, v31, v201
	global_store_short v219, v153, s[20:21]
	s_mov_b32 s97, 16
	s_branch .Lgs_next
.Lgs_s2_state:
	v_cvt_pk_bf16_f32 v154, v0, v1
	v_cvt_pk_bf16_f32 v155, v2, v3
	v_cvt_pk_bf16_f32 v156, v4, v5
	v_cvt_pk_bf16_f32 v157, v6, v7
	v_cvt_pk_bf16_f32 v158, v8, v9
	v_cvt_pk_bf16_f32 v159, v10, v11
	v_cvt_pk_bf16_f32 v160, v12, v13
	v_cvt_pk_bf16_f32 v161, v14, v15
	v_xor_b32_e32 v198, 16, v250
	v_xor_b32_e32 v199, 32, v250
	v_xor_b32_e32 v200, 48, v250
	ds_write_b64 v250, v[154:155]
	ds_write_b64 v198, v[156:157]
	ds_write_b64 v199, v[158:159]
	ds_write_b64 v200, v[160:161]
.Lgs_next:
	s_add_u32 s54, s54, 1
	s_cmp_lt_u32 s54, 68
	s_cbranch_scc1 .Lgs_chunk
	s_waitcnt vmcnt(0) lgkmcnt(0)
	s_barrier
	s_add_i32 s53, s53, s71
	s_cmpk_gt_i32 s53, 0xff
	s_cbranch_scc0 .Lgs_unit
